# stack + FFN-up/QKV: accumulator zeroing (128 v_mov per unit) removed; first half K-iteration peeled with SrcC=0
# baseline (speedup 1.0000x reference)
.LBB0_166:
	s_ashr_i32 s27, s26, 31
	s_lshl_b64 s[28:29], s[26:27], 19
	s_add_u32 s28, s69, s28
	s_addc_u32 s29, s78, s29
	s_and_b64 s[30:31], s[4:5], exec
	s_cselect_b32 s2, s29, s39
	s_cselect_b32 s15, s28, s38
	s_ashr_i32 s25, s24, 31
	s_lshl_b64 s[30:31], s[24:25], 19
	s_add_u32 s30, s7, s30
	s_addc_u32 s31, s79, s31
	s_and_b64 s[42:43], s[4:5], exec
	s_cselect_b32 s25, s31, s63
	s_cselect_b32 s27, s30, s62
	s_add_u32 s38, s38, 0x40080
	s_addc_u32 s39, s39, 0
	s_add_u32 s35, s62, 0x100
	s_addc_u32 s42, s63, 0
	s_mov_b32 s43, -2
	s_waitcnt vmcnt(0)
	s_add_u32 s48, s38, 0xfffc0080
	s_addc_u32 s49, s39, -1
	s_add_i32 s59, 0, 0x10000
	s_cmp_eq_u32 s43, 12
	s_cselect_b32 s65, s2, s49
	s_cselect_b32 s64, s15, s48
	v_add_u32_e32 v142, s59, v145
	s_cselect_b32 s63, s25, s42
	s_cselect_b32 s62, s27, s35
	s_add_i32 s66, 0, 0x14000
	ds_read_b128 v[148:151], v142
	ds_read_b128 v[152:155], v142 offset:1024
	ds_read_b128 v[156:159], v142 offset:2048
	ds_read_b128 v[160:163], v142 offset:3072
	v_add_u32_e32 v142, s66, v145
	ds_read_b128 v[164:167], v142
	ds_read_b128 v[168:171], v142 offset:1024
	ds_read_b128 v[172:175], v142 offset:2048
	ds_read_b128 v[180:183], v142 offset:3072
	v_lshl_add_u64 v[142:143], s[38:39], 0, v[136:137]
	s_add_i32 m0, s37, 0xc000
	ds_read_b128 v[184:187], v147
	ds_read_b128 v[188:191], v147 offset:1024
	ds_read_b128 v[192:195], v147 offset:2048
	ds_read_b128 v[196:199], v147 offset:3072
	ds_read_b128 v[200:203], v147 offset:4096
	ds_read_b128 v[204:207], v147 offset:5120
	ds_read_b128 v[208:211], v147 offset:6144
	ds_read_b128 v[212:215], v147 offset:7168
	global_load_lds_dwordx4 v[142:143], off
	v_lshl_add_u64 v[142:143], s[38:39], 0, v[138:139]
	s_add_i32 m0, s37, 0xe000
	s_nop 0
	global_load_lds_dwordx4 v[142:143], off
	s_waitcnt vmcnt(8)
	s_waitcnt lgkmcnt(0)
	s_barrier
	s_setprio 1
	s_waitcnt lgkmcnt(0)
	v_mfma_f32_16x16x32_bf16 v[126:129], v[148:151], v[184:187], 0
	v_mfma_f32_16x16x32_bf16 v[118:121], v[156:159], v[184:187], 0
	v_mfma_f32_16x16x32_bf16 v[110:113], v[148:151], v[192:195], 0
	v_mfma_f32_16x16x32_bf16 v[102:105], v[156:159], v[192:195], 0
	v_mfma_f32_16x16x32_bf16 v[94:97], v[148:151], v[200:203], 0
	v_mfma_f32_16x16x32_bf16 v[86:89], v[156:159], v[200:203], 0
	v_mfma_f32_16x16x32_bf16 v[78:81], v[148:151], v[208:211], 0
	v_mfma_f32_16x16x32_bf16 v[70:73], v[156:159], v[208:211], 0
	v_mfma_f32_16x16x32_bf16 v[126:129], v[152:155], v[188:191], v[126:129]
	v_mfma_f32_16x16x32_bf16 v[118:121], v[160:163], v[188:191], v[118:121]
	v_mfma_f32_16x16x32_bf16 v[110:113], v[152:155], v[196:199], v[110:113]
	v_mfma_f32_16x16x32_bf16 v[102:105], v[160:163], v[196:199], v[102:105]
	v_mfma_f32_16x16x32_bf16 v[94:97], v[152:155], v[204:207], v[94:97]
	v_mfma_f32_16x16x32_bf16 v[86:89], v[160:163], v[204:207], v[86:89]
	v_mfma_f32_16x16x32_bf16 v[78:81], v[152:155], v[212:215], v[78:81]
	v_mfma_f32_16x16x32_bf16 v[70:73], v[160:163], v[212:215], v[70:73]
	s_setprio 0
	s_setprio 1
	v_mfma_f32_16x16x32_bf16 v[122:125], v[164:167], v[184:187], 0
	v_mfma_f32_16x16x32_bf16 v[114:117], v[172:175], v[184:187], 0
	v_mfma_f32_16x16x32_bf16 v[106:109], v[164:167], v[192:195], 0
	v_mfma_f32_16x16x32_bf16 v[98:101], v[172:175], v[192:195], 0
	v_mfma_f32_16x16x32_bf16 v[90:93], v[164:167], v[200:203], 0
	v_mfma_f32_16x16x32_bf16 v[82:85], v[172:175], v[200:203], 0
	v_mfma_f32_16x16x32_bf16 v[74:77], v[164:167], v[208:211], 0
	v_mfma_f32_16x16x32_bf16 v[66:69], v[172:175], v[208:211], 0
	v_mfma_f32_16x16x32_bf16 v[122:125], v[168:171], v[188:191], v[122:125]
	v_mfma_f32_16x16x32_bf16 v[114:117], v[180:183], v[188:191], v[114:117]
	v_mfma_f32_16x16x32_bf16 v[106:109], v[168:171], v[196:199], v[106:109]
	v_mfma_f32_16x16x32_bf16 v[98:101], v[180:183], v[196:199], v[98:101]
	v_mfma_f32_16x16x32_bf16 v[90:93], v[168:171], v[204:207], v[90:93]
	v_mfma_f32_16x16x32_bf16 v[82:85], v[180:183], v[204:207], v[82:85]
	v_mfma_f32_16x16x32_bf16 v[74:77], v[168:171], v[212:215], v[74:77]
	v_mfma_f32_16x16x32_bf16 v[66:69], v[180:183], v[212:215], v[66:69]
	s_setprio 0
	s_barrier
	s_add_i32 s48, s59, s80
	v_lshl_add_u64 v[142:143], s[62:63], 0, v[0:1]
	s_mov_b32 m0, s48
	ds_read_b128 v[184:187], v147 offset:16384
	ds_read_b128 v[188:191], v147 offset:17408
	ds_read_b128 v[192:195], v147 offset:18432
	ds_read_b128 v[196:199], v147 offset:19456
	ds_read_b128 v[200:203], v147 offset:20480
	ds_read_b128 v[204:207], v147 offset:21504
	ds_read_b128 v[208:211], v147 offset:22528
	ds_read_b128 v[212:215], v147 offset:23552
	global_load_lds_dwordx4 v[142:143], off
	s_add_i32 m0, s48, 0x2000
	s_add_u32 s48, s62, 0x40000
	v_lshl_add_u64 v[176:177], s[62:63], 0, v[130:131]
	s_addc_u32 s49, s63, 0
	s_add_i32 s59, s66, s80
	global_load_lds_dwordx4 v[176:177], off
	v_lshl_add_u64 v[216:217], s[48:49], 0, v[0:1]
	s_mov_b32 m0, s59
	v_lshl_add_u64 v[218:219], s[64:65], 0, v[132:133]
	global_load_lds_dwordx4 v[216:217], off
	v_lshl_add_u64 v[216:217], s[48:49], 0, v[130:131]
	s_add_i32 m0, s59, 0x2000
	s_nop 0
	global_load_lds_dwordx4 v[216:217], off
	v_lshl_add_u64 v[216:217], s[64:65], 0, v[134:135]
	s_mov_b32 m0, s37
	s_nop 0
	global_load_lds_dwordx4 v[216:217], off
	s_mov_b32 m0, s81
	s_nop 0
	global_load_lds_dwordx4 v[218:219], off
	s_waitcnt vmcnt(8)
	s_waitcnt lgkmcnt(0)
	s_barrier
	s_setprio 1
	s_waitcnt lgkmcnt(0)
	v_mfma_f32_16x16x32_bf16 v[62:65], v[148:151], v[184:187], 0
	v_mfma_f32_16x16x32_bf16 v[54:57], v[156:159], v[184:187], 0
	v_mfma_f32_16x16x32_bf16 v[46:49], v[148:151], v[192:195], 0
	v_mfma_f32_16x16x32_bf16 v[38:41], v[156:159], v[192:195], 0
	v_mfma_f32_16x16x32_bf16 v[30:33], v[148:151], v[200:203], 0
	v_mfma_f32_16x16x32_bf16 v[22:25], v[156:159], v[200:203], 0
	v_mfma_f32_16x16x32_bf16 v[14:17], v[148:151], v[208:211], 0
	v_mfma_f32_16x16x32_bf16 v[6:9], v[156:159], v[208:211], 0
	v_mfma_f32_16x16x32_bf16 v[62:65], v[152:155], v[188:191], v[62:65]
	v_mfma_f32_16x16x32_bf16 v[54:57], v[160:163], v[188:191], v[54:57]
	v_mfma_f32_16x16x32_bf16 v[46:49], v[152:155], v[196:199], v[46:49]
	v_mfma_f32_16x16x32_bf16 v[38:41], v[160:163], v[196:199], v[38:41]
	v_mfma_f32_16x16x32_bf16 v[30:33], v[152:155], v[204:207], v[30:33]
	v_mfma_f32_16x16x32_bf16 v[22:25], v[160:163], v[204:207], v[22:25]
	v_mfma_f32_16x16x32_bf16 v[14:17], v[152:155], v[212:215], v[14:17]
	v_mfma_f32_16x16x32_bf16 v[6:9], v[160:163], v[212:215], v[6:9]
	s_setprio 0
	s_setprio 1
	v_mfma_f32_16x16x32_bf16 v[58:61], v[164:167], v[184:187], 0
	v_mfma_f32_16x16x32_bf16 v[50:53], v[172:175], v[184:187], 0
	v_mfma_f32_16x16x32_bf16 v[42:45], v[164:167], v[192:195], 0
	v_mfma_f32_16x16x32_bf16 v[34:37], v[172:175], v[192:195], 0
	v_mfma_f32_16x16x32_bf16 v[26:29], v[164:167], v[200:203], 0
	v_mfma_f32_16x16x32_bf16 v[18:21], v[172:175], v[200:203], 0
	v_mfma_f32_16x16x32_bf16 v[10:13], v[164:167], v[208:211], 0
	v_mfma_f32_16x16x32_bf16 v[2:5], v[172:175], v[208:211], 0
	v_mfma_f32_16x16x32_bf16 v[58:61], v[168:171], v[188:191], v[58:61]
	v_mfma_f32_16x16x32_bf16 v[50:53], v[180:183], v[188:191], v[50:53]
	v_mfma_f32_16x16x32_bf16 v[42:45], v[168:171], v[196:199], v[42:45]
	v_mfma_f32_16x16x32_bf16 v[34:37], v[180:183], v[196:199], v[34:37]
	v_mfma_f32_16x16x32_bf16 v[26:29], v[168:171], v[204:207], v[26:29]
	v_mfma_f32_16x16x32_bf16 v[18:21], v[180:183], v[204:207], v[18:21]
	v_mfma_f32_16x16x32_bf16 v[10:13], v[168:171], v[212:215], v[10:13]
	v_mfma_f32_16x16x32_bf16 v[2:5], v[180:183], v[212:215], v[2:5]
	s_setprio 0
	s_barrier
	s_branch .Lmy_mid_up

.Lmy_mid_up:
	s_add_i32 s59, 0, 0x18000
	s_add_i32 s66, 0, 0x1c000
	v_add_u32_e32 v160, s59, v145
	v_add_u32_e32 v180, s66, v145
	ds_read_b128 v[148:151], v160
	ds_read_b128 v[152:155], v160 offset:1024
	ds_read_b128 v[156:159], v160 offset:2048
	ds_read_b128 v[160:163], v160 offset:3072
	ds_read_b128 v[164:167], v180
	ds_read_b128 v[168:171], v180 offset:1024
	ds_read_b128 v[172:175], v180 offset:2048
	ds_read_b128 v[180:183], v180 offset:3072
	s_add_u32 s48, s64, 0x40000
	s_addc_u32 s49, s65, 0
	s_mov_b32 m0, s84
	v_lshl_add_u64 v[220:221], s[48:49], 0, v[134:135]
	ds_read_b128 v[184:187], v147 offset:32768
	ds_read_b128 v[188:191], v147 offset:33792
	ds_read_b128 v[192:195], v147 offset:34816
	ds_read_b128 v[196:199], v147 offset:35840
	ds_read_b128 v[200:203], v147 offset:36864
	ds_read_b128 v[204:207], v147 offset:37888
	ds_read_b128 v[208:211], v147 offset:38912
	ds_read_b128 v[212:215], v147 offset:39936
	global_load_lds_dwordx4 v[220:221], off
	v_lshl_add_u64 v[220:221], s[48:49], 0, v[132:133]
	s_mov_b32 m0, s85
	s_nop 0
	global_load_lds_dwordx4 v[220:221], off
	s_waitcnt vmcnt(8)
	s_waitcnt lgkmcnt(0)
	s_barrier
	s_setprio 1
	s_waitcnt lgkmcnt(0)
	v_mfma_f32_16x16x32_bf16 v[126:129], v[148:151], v[184:187], v[126:129]
	v_mfma_f32_16x16x32_bf16 v[118:121], v[156:159], v[184:187], v[118:121]
	v_mfma_f32_16x16x32_bf16 v[110:113], v[148:151], v[192:195], v[110:113]
	v_mfma_f32_16x16x32_bf16 v[102:105], v[156:159], v[192:195], v[102:105]
	v_mfma_f32_16x16x32_bf16 v[94:97], v[148:151], v[200:203], v[94:97]
	v_mfma_f32_16x16x32_bf16 v[86:89], v[156:159], v[200:203], v[86:89]
	v_mfma_f32_16x16x32_bf16 v[78:81], v[148:151], v[208:211], v[78:81]
	v_mfma_f32_16x16x32_bf16 v[70:73], v[156:159], v[208:211], v[70:73]
	v_mfma_f32_16x16x32_bf16 v[126:129], v[152:155], v[188:191], v[126:129]
	v_mfma_f32_16x16x32_bf16 v[118:121], v[160:163], v[188:191], v[118:121]
	v_mfma_f32_16x16x32_bf16 v[110:113], v[152:155], v[196:199], v[110:113]
	v_mfma_f32_16x16x32_bf16 v[102:105], v[160:163], v[196:199], v[102:105]
	v_mfma_f32_16x16x32_bf16 v[94:97], v[152:155], v[204:207], v[94:97]
	v_mfma_f32_16x16x32_bf16 v[86:89], v[160:163], v[204:207], v[86:89]
	v_mfma_f32_16x16x32_bf16 v[78:81], v[152:155], v[212:215], v[78:81]
	v_mfma_f32_16x16x32_bf16 v[70:73], v[160:163], v[212:215], v[70:73]
	s_setprio 0
	s_setprio 1
	v_mfma_f32_16x16x32_bf16 v[122:125], v[164:167], v[184:187], v[122:125]
	v_mfma_f32_16x16x32_bf16 v[114:117], v[172:175], v[184:187], v[114:117]
	v_mfma_f32_16x16x32_bf16 v[106:109], v[164:167], v[192:195], v[106:109]
	v_mfma_f32_16x16x32_bf16 v[98:101], v[172:175], v[192:195], v[98:101]
	v_mfma_f32_16x16x32_bf16 v[90:93], v[164:167], v[200:203], v[90:93]
	v_mfma_f32_16x16x32_bf16 v[82:85], v[172:175], v[200:203], v[82:85]
	v_mfma_f32_16x16x32_bf16 v[74:77], v[164:167], v[208:211], v[74:77]
	v_mfma_f32_16x16x32_bf16 v[66:69], v[172:175], v[208:211], v[66:69]
	v_mfma_f32_16x16x32_bf16 v[122:125], v[168:171], v[188:191], v[122:125]
	v_mfma_f32_16x16x32_bf16 v[114:117], v[180:183], v[188:191], v[114:117]
	v_mfma_f32_16x16x32_bf16 v[106:109], v[168:171], v[196:199], v[106:109]
	v_mfma_f32_16x16x32_bf16 v[98:101], v[180:183], v[196:199], v[98:101]
	v_mfma_f32_16x16x32_bf16 v[90:93], v[168:171], v[204:207], v[90:93]
	v_mfma_f32_16x16x32_bf16 v[82:85], v[180:183], v[204:207], v[82:85]
	v_mfma_f32_16x16x32_bf16 v[74:77], v[168:171], v[212:215], v[74:77]
	v_mfma_f32_16x16x32_bf16 v[66:69], v[180:183], v[212:215], v[66:69]
	s_setprio 0
	s_barrier
	s_add_i32 s48, s59, s80
	v_lshl_add_u64 v[142:143], v[142:143], 0, s[74:75]
	s_mov_b32 m0, s48
	ds_read_b128 v[184:187], v147 offset:49152
	ds_read_b128 v[188:191], v147 offset:50176
	ds_read_b128 v[192:195], v147 offset:51200
	ds_read_b128 v[196:199], v147 offset:52224
	ds_read_b128 v[200:203], v147 offset:53248
	ds_read_b128 v[204:207], v147 offset:54272
	ds_read_b128 v[208:211], v147 offset:55296
	ds_read_b128 v[212:215], v147 offset:56320
	global_load_lds_dwordx4 v[142:143], off
	s_add_i32 m0, s48, 0x2000
	s_add_u32 s48, s62, 0x40080
	v_lshl_add_u64 v[142:143], v[176:177], 0, s[74:75]
	s_addc_u32 s49, s63, 0
	s_add_i32 s59, s66, s80
	global_load_lds_dwordx4 v[142:143], off
	v_lshl_add_u64 v[142:143], s[48:49], 0, v[0:1]
	s_mov_b32 m0, s59
	s_nop 0
	global_load_lds_dwordx4 v[142:143], off
	v_lshl_add_u64 v[142:143], s[48:49], 0, v[130:131]
	s_add_i32 m0, s59, 0x2000
	s_nop 0
	global_load_lds_dwordx4 v[142:143], off
	v_lshl_add_u64 v[142:143], v[216:217], 0, s[74:75]
	s_mov_b32 m0, s86
	s_nop 0
	global_load_lds_dwordx4 v[142:143], off
	v_lshl_add_u64 v[142:143], v[218:219], 0, s[74:75]
	s_mov_b32 m0, s87
	s_nop 0
	global_load_lds_dwordx4 v[142:143], off
	s_waitcnt vmcnt(8)
	s_waitcnt lgkmcnt(0)
	s_barrier
	s_setprio 1
	s_waitcnt lgkmcnt(0)
	v_mfma_f32_16x16x32_bf16 v[62:65], v[148:151], v[184:187], v[62:65]
	v_mfma_f32_16x16x32_bf16 v[54:57], v[156:159], v[184:187], v[54:57]
	v_mfma_f32_16x16x32_bf16 v[46:49], v[148:151], v[192:195], v[46:49]
	v_mfma_f32_16x16x32_bf16 v[38:41], v[156:159], v[192:195], v[38:41]
	v_mfma_f32_16x16x32_bf16 v[30:33], v[148:151], v[200:203], v[30:33]
	v_mfma_f32_16x16x32_bf16 v[22:25], v[156:159], v[200:203], v[22:25]
	v_mfma_f32_16x16x32_bf16 v[14:17], v[148:151], v[208:211], v[14:17]
	v_mfma_f32_16x16x32_bf16 v[6:9], v[156:159], v[208:211], v[6:9]
	v_mfma_f32_16x16x32_bf16 v[62:65], v[152:155], v[188:191], v[62:65]
	v_mfma_f32_16x16x32_bf16 v[54:57], v[160:163], v[188:191], v[54:57]
	v_mfma_f32_16x16x32_bf16 v[46:49], v[152:155], v[196:199], v[46:49]
	v_mfma_f32_16x16x32_bf16 v[38:41], v[160:163], v[196:199], v[38:41]
	v_mfma_f32_16x16x32_bf16 v[30:33], v[152:155], v[204:207], v[30:33]
	v_mfma_f32_16x16x32_bf16 v[22:25], v[160:163], v[204:207], v[22:25]
	v_mfma_f32_16x16x32_bf16 v[14:17], v[152:155], v[212:215], v[14:17]
	v_mfma_f32_16x16x32_bf16 v[6:9], v[160:163], v[212:215], v[6:9]
	s_setprio 0
	s_setprio 1
	v_mfma_f32_16x16x32_bf16 v[58:61], v[164:167], v[184:187], v[58:61]
	v_mfma_f32_16x16x32_bf16 v[50:53], v[172:175], v[184:187], v[50:53]
	v_mfma_f32_16x16x32_bf16 v[42:45], v[164:167], v[192:195], v[42:45]
	v_mfma_f32_16x16x32_bf16 v[34:37], v[172:175], v[192:195], v[34:37]
	v_mfma_f32_16x16x32_bf16 v[26:29], v[164:167], v[200:203], v[26:29]
	v_mfma_f32_16x16x32_bf16 v[18:21], v[172:175], v[200:203], v[18:21]
	v_mfma_f32_16x16x32_bf16 v[10:13], v[164:167], v[208:211], v[10:13]
	v_mfma_f32_16x16x32_bf16 v[2:5], v[172:175], v[208:211], v[2:5]
	v_mfma_f32_16x16x32_bf16 v[58:61], v[168:171], v[188:191], v[58:61]
	v_mfma_f32_16x16x32_bf16 v[50:53], v[180:183], v[188:191], v[50:53]
	v_mfma_f32_16x16x32_bf16 v[42:45], v[168:171], v[196:199], v[42:45]
	v_mfma_f32_16x16x32_bf16 v[34:37], v[180:183], v[196:199], v[34:37]
	v_mfma_f32_16x16x32_bf16 v[26:29], v[168:171], v[204:207], v[26:29]
	v_mfma_f32_16x16x32_bf16 v[18:21], v[180:183], v[204:207], v[18:21]
	v_mfma_f32_16x16x32_bf16 v[10:13], v[168:171], v[212:215], v[10:13]
	v_mfma_f32_16x16x32_bf16 v[2:5], v[180:183], v[212:215], v[2:5]
	s_setprio 0
	s_barrier
	s_add_i32 s43, s43, 2
	s_add_u32 s38, s38, 0x100
	s_addc_u32 s39, s39, 0
	s_add_u32 s35, s35, 0x100
	s_addc_u32 s42, s42, 0
	s_cmp_gt_u32 s43, 13
	s_cbranch_scc0 .LBB0_167
	s_and_b64 vcc, exec, s[22:23]
	s_cbranch_vccz .LBB0_170
	s_barrier

.LBB0_707:
	s_ashr_i32 s25, s24, 31
	s_lshl_b64 s[26:27], s[24:25], 19
	s_add_u32 s26, s62, s26
	s_addc_u32 s27, s63, s27
	s_and_b64 s[28:29], s[8:9], exec
	s_cselect_b32 s2, s27, s31
	s_cselect_b32 s11, s26, s30
	s_ashr_i32 s23, s22, 31
	s_lshl_b64 s[28:29], s[22:23], 19
	s_add_u32 s28, s64, s28
	s_addc_u32 s29, s65, s29
	s_and_b64 s[38:39], s[8:9], exec
	s_cselect_b32 s13, s29, s37
	s_cselect_b32 s23, s28, s36
	s_add_u32 s30, s30, 0x40080
	s_addc_u32 s31, s31, 0
	s_add_u32 s25, s36, 0x100
	s_addc_u32 s35, s37, 0
	s_mov_b32 s42, -2
	s_add_u32 s33, s30, 0xfffc0080
	s_addc_u32 s36, s31, -1
	s_add_i32 s43, 0, 0x10000
	s_cmp_eq_u32 s42, 12
	s_cselect_b32 s39, s2, s36
	s_cselect_b32 s38, s11, s33
	v_add_u32_e32 v155, s43, v149
	s_cselect_b32 s37, s13, s35
	s_cselect_b32 s36, s23, s25
	s_add_i32 s33, 0, 0x14000
	ds_read_b128 v[130:133], v155
	ds_read_b128 v[156:159], v155 offset:1024
	ds_read_b128 v[160:163], v155 offset:2048
	ds_read_b128 v[164:167], v155 offset:3072
	v_add_u32_e32 v155, s33, v149
	ds_read_b128 v[168:171], v155
	ds_read_b128 v[172:175], v155 offset:1024
	ds_read_b128 v[180:183], v155 offset:2048
	ds_read_b128 v[184:187], v155 offset:3072
	v_lshl_add_u64 v[176:177], s[30:31], 0, v[144:145]
	s_add_i32 m0, s69, 0xc000
	ds_read_b128 v[188:191], v153
	ds_read_b128 v[192:195], v153 offset:1024
	ds_read_b128 v[196:199], v153 offset:2048
	ds_read_b128 v[200:203], v153 offset:3072
	ds_read_b128 v[204:207], v153 offset:4096
	ds_read_b128 v[208:211], v153 offset:5120
	ds_read_b128 v[212:215], v153 offset:6144
	ds_read_b128 v[216:219], v153 offset:7168
	global_load_lds_dwordx4 v[176:177], off
	v_lshl_add_u64 v[176:177], s[30:31], 0, v[146:147]
	s_add_i32 m0, s69, 0xe000
	s_nop 0
	global_load_lds_dwordx4 v[176:177], off
	s_waitcnt vmcnt(8)
	s_waitcnt lgkmcnt(0)
	s_barrier
	s_setprio 1
	s_waitcnt lgkmcnt(0)
	v_mfma_f32_16x16x32_bf16 v[126:129], v[130:133], v[188:191], 0
	v_mfma_f32_16x16x32_bf16 v[122:125], v[160:163], v[188:191], 0
	v_mfma_f32_16x16x32_bf16 v[118:121], v[130:133], v[196:199], 0
	v_mfma_f32_16x16x32_bf16 v[114:117], v[160:163], v[196:199], 0
	v_mfma_f32_16x16x32_bf16 v[110:113], v[130:133], v[204:207], 0
	v_mfma_f32_16x16x32_bf16 v[106:109], v[160:163], v[204:207], 0
	v_mfma_f32_16x16x32_bf16 v[102:105], v[130:133], v[212:215], 0
	v_mfma_f32_16x16x32_bf16 v[98:101], v[160:163], v[212:215], 0
	v_mfma_f32_16x16x32_bf16 v[126:129], v[156:159], v[192:195], v[126:129]
	v_mfma_f32_16x16x32_bf16 v[122:125], v[164:167], v[192:195], v[122:125]
	v_mfma_f32_16x16x32_bf16 v[118:121], v[156:159], v[200:203], v[118:121]
	v_mfma_f32_16x16x32_bf16 v[114:117], v[164:167], v[200:203], v[114:117]
	v_mfma_f32_16x16x32_bf16 v[110:113], v[156:159], v[208:211], v[110:113]
	v_mfma_f32_16x16x32_bf16 v[106:109], v[164:167], v[208:211], v[106:109]
	v_mfma_f32_16x16x32_bf16 v[102:105], v[156:159], v[216:219], v[102:105]
	v_mfma_f32_16x16x32_bf16 v[98:101], v[164:167], v[216:219], v[98:101]
	s_setprio 0
	s_setprio 1
	v_mfma_f32_16x16x32_bf16 v[62:65], v[168:171], v[188:191], 0
	v_mfma_f32_16x16x32_bf16 v[58:61], v[180:183], v[188:191], 0
	v_mfma_f32_16x16x32_bf16 v[54:57], v[168:171], v[196:199], 0
	v_mfma_f32_16x16x32_bf16 v[50:53], v[180:183], v[196:199], 0
	v_mfma_f32_16x16x32_bf16 v[46:49], v[168:171], v[204:207], 0
	v_mfma_f32_16x16x32_bf16 v[42:45], v[180:183], v[204:207], 0
	v_mfma_f32_16x16x32_bf16 v[38:41], v[168:171], v[212:215], 0
	v_mfma_f32_16x16x32_bf16 v[34:37], v[180:183], v[212:215], 0
	v_mfma_f32_16x16x32_bf16 v[62:65], v[172:175], v[192:195], v[62:65]
	v_mfma_f32_16x16x32_bf16 v[58:61], v[184:187], v[192:195], v[58:61]
	v_mfma_f32_16x16x32_bf16 v[54:57], v[172:175], v[200:203], v[54:57]
	v_mfma_f32_16x16x32_bf16 v[50:53], v[184:187], v[200:203], v[50:53]
	v_mfma_f32_16x16x32_bf16 v[46:49], v[172:175], v[208:211], v[46:49]
	v_mfma_f32_16x16x32_bf16 v[42:45], v[184:187], v[208:211], v[42:45]
	v_mfma_f32_16x16x32_bf16 v[38:41], v[172:175], v[216:219], v[38:41]
	v_mfma_f32_16x16x32_bf16 v[34:37], v[184:187], v[216:219], v[34:37]
	s_setprio 0
	s_barrier
	s_add_i32 s43, s43, s68
	v_lshl_add_u64 v[176:177], s[36:37], 0, v[0:1]
	s_mov_b32 m0, s43
	ds_read_b128 v[188:191], v153 offset:16384
	ds_read_b128 v[192:195], v153 offset:17408
	ds_read_b128 v[196:199], v153 offset:18432
	ds_read_b128 v[200:203], v153 offset:19456
	ds_read_b128 v[204:207], v153 offset:20480
	ds_read_b128 v[208:211], v153 offset:21504
	ds_read_b128 v[212:215], v153 offset:22528
	ds_read_b128 v[216:219], v153 offset:23552
	global_load_lds_dwordx4 v[176:177], off
	s_add_i32 m0, s43, 0x2000
	s_add_u32 s48, s36, 0x40000
	v_lshl_add_u64 v[220:221], s[36:37], 0, v[138:139]
	s_addc_u32 s49, s37, 0
	s_add_i32 s33, s33, s68
	global_load_lds_dwordx4 v[220:221], off
	v_lshl_add_u64 v[222:223], s[48:49], 0, v[0:1]
	s_mov_b32 m0, s33
	v_lshl_add_u64 v[224:225], s[38:39], 0, v[136:137]
	global_load_lds_dwordx4 v[222:223], off
	v_lshl_add_u64 v[222:223], s[48:49], 0, v[138:139]
	s_add_i32 m0, s33, 0x2000
	s_nop 0
	global_load_lds_dwordx4 v[222:223], off
	v_lshl_add_u64 v[222:223], s[38:39], 0, v[134:135]
	s_mov_b32 m0, s69
	s_nop 0
	global_load_lds_dwordx4 v[222:223], off
	s_mov_b32 m0, s78
	s_nop 0
	global_load_lds_dwordx4 v[224:225], off
	s_waitcnt vmcnt(8)
	s_waitcnt lgkmcnt(0)
	s_barrier
	s_setprio 1
	s_waitcnt lgkmcnt(0)
	v_mfma_f32_16x16x32_bf16 v[94:97], v[130:133], v[188:191], 0
	v_mfma_f32_16x16x32_bf16 v[90:93], v[160:163], v[188:191], 0
	v_mfma_f32_16x16x32_bf16 v[86:89], v[130:133], v[196:199], 0
	v_mfma_f32_16x16x32_bf16 v[82:85], v[160:163], v[196:199], 0
	v_mfma_f32_16x16x32_bf16 v[78:81], v[130:133], v[204:207], 0
	v_mfma_f32_16x16x32_bf16 v[74:77], v[160:163], v[204:207], 0
	v_mfma_f32_16x16x32_bf16 v[70:73], v[130:133], v[212:215], 0
	v_mfma_f32_16x16x32_bf16 v[66:69], v[160:163], v[212:215], 0
	v_mfma_f32_16x16x32_bf16 v[94:97], v[156:159], v[192:195], v[94:97]
	v_mfma_f32_16x16x32_bf16 v[90:93], v[164:167], v[192:195], v[90:93]
	v_mfma_f32_16x16x32_bf16 v[86:89], v[156:159], v[200:203], v[86:89]
	v_mfma_f32_16x16x32_bf16 v[82:85], v[164:167], v[200:203], v[82:85]
	v_mfma_f32_16x16x32_bf16 v[78:81], v[156:159], v[208:211], v[78:81]
	v_mfma_f32_16x16x32_bf16 v[74:77], v[164:167], v[208:211], v[74:77]
	v_mfma_f32_16x16x32_bf16 v[70:73], v[156:159], v[216:219], v[70:73]
	v_mfma_f32_16x16x32_bf16 v[66:69], v[164:167], v[216:219], v[66:69]
	s_setprio 0
	s_setprio 1
	v_mfma_f32_16x16x32_bf16 v[30:33], v[168:171], v[188:191], 0
	v_mfma_f32_16x16x32_bf16 v[26:29], v[180:183], v[188:191], 0
	v_mfma_f32_16x16x32_bf16 v[22:25], v[168:171], v[196:199], 0
	v_mfma_f32_16x16x32_bf16 v[18:21], v[180:183], v[196:199], 0
	v_mfma_f32_16x16x32_bf16 v[14:17], v[168:171], v[204:207], 0
	v_mfma_f32_16x16x32_bf16 v[10:13], v[180:183], v[204:207], 0
	v_mfma_f32_16x16x32_bf16 v[6:9], v[168:171], v[212:215], 0
	v_mfma_f32_16x16x32_bf16 v[2:5], v[180:183], v[212:215], 0
	v_mfma_f32_16x16x32_bf16 v[30:33], v[172:175], v[192:195], v[30:33]
	v_mfma_f32_16x16x32_bf16 v[26:29], v[184:187], v[192:195], v[26:29]
	v_mfma_f32_16x16x32_bf16 v[22:25], v[172:175], v[200:203], v[22:25]
	v_mfma_f32_16x16x32_bf16 v[18:21], v[184:187], v[200:203], v[18:21]
	v_mfma_f32_16x16x32_bf16 v[14:17], v[172:175], v[208:211], v[14:17]
	v_mfma_f32_16x16x32_bf16 v[10:13], v[184:187], v[208:211], v[10:13]
	v_mfma_f32_16x16x32_bf16 v[6:9], v[172:175], v[216:219], v[6:9]
	v_mfma_f32_16x16x32_bf16 v[2:5], v[184:187], v[216:219], v[2:5]
	s_setprio 0
	s_barrier
	s_branch .Lmy_mid_qkv

.Lmy_mid_qkv:
	s_add_i32 s33, 0, 0x18000
	v_add_u32_e32 v155, s33, v149
	s_add_i32 s43, 0, 0x1c000
	ds_read_b128 v[130:133], v155
	ds_read_b128 v[156:159], v155 offset:1024
	ds_read_b128 v[160:163], v155 offset:2048
	ds_read_b128 v[164:167], v155 offset:3072
	v_add_u32_e32 v155, s43, v149
	ds_read_b128 v[168:171], v155
	ds_read_b128 v[172:175], v155 offset:1024
	ds_read_b128 v[180:183], v155 offset:2048
	ds_read_b128 v[184:187], v155 offset:3072
	s_add_u32 s38, s38, 0x40000
	s_addc_u32 s39, s39, 0
	s_mov_b32 m0, s79
	v_lshl_add_u64 v[226:227], s[38:39], 0, v[134:135]
	ds_read_b128 v[188:191], v153 offset:32768
	ds_read_b128 v[192:195], v153 offset:33792
	ds_read_b128 v[196:199], v153 offset:34816
	ds_read_b128 v[200:203], v153 offset:35840
	ds_read_b128 v[204:207], v153 offset:36864
	ds_read_b128 v[208:211], v153 offset:37888
	ds_read_b128 v[212:215], v153 offset:38912
	ds_read_b128 v[216:219], v153 offset:39936
	global_load_lds_dwordx4 v[226:227], off
	v_lshl_add_u64 v[226:227], s[38:39], 0, v[136:137]
	s_mov_b32 m0, s80
	s_nop 0
	global_load_lds_dwordx4 v[226:227], off
	s_waitcnt vmcnt(8)
	s_waitcnt lgkmcnt(0)
	s_barrier
	s_setprio 1
	s_waitcnt lgkmcnt(0)
	v_mfma_f32_16x16x32_bf16 v[126:129], v[130:133], v[188:191], v[126:129]
	v_mfma_f32_16x16x32_bf16 v[122:125], v[160:163], v[188:191], v[122:125]
	v_mfma_f32_16x16x32_bf16 v[118:121], v[130:133], v[196:199], v[118:121]
	v_mfma_f32_16x16x32_bf16 v[114:117], v[160:163], v[196:199], v[114:117]
	v_mfma_f32_16x16x32_bf16 v[110:113], v[130:133], v[204:207], v[110:113]
	v_mfma_f32_16x16x32_bf16 v[106:109], v[160:163], v[204:207], v[106:109]
	v_mfma_f32_16x16x32_bf16 v[102:105], v[130:133], v[212:215], v[102:105]
	v_mfma_f32_16x16x32_bf16 v[98:101], v[160:163], v[212:215], v[98:101]
	v_mfma_f32_16x16x32_bf16 v[126:129], v[156:159], v[192:195], v[126:129]
	v_mfma_f32_16x16x32_bf16 v[122:125], v[164:167], v[192:195], v[122:125]
	v_mfma_f32_16x16x32_bf16 v[118:121], v[156:159], v[200:203], v[118:121]
	v_mfma_f32_16x16x32_bf16 v[114:117], v[164:167], v[200:203], v[114:117]
	v_mfma_f32_16x16x32_bf16 v[110:113], v[156:159], v[208:211], v[110:113]
	v_mfma_f32_16x16x32_bf16 v[106:109], v[164:167], v[208:211], v[106:109]
	v_mfma_f32_16x16x32_bf16 v[102:105], v[156:159], v[216:219], v[102:105]
	v_mfma_f32_16x16x32_bf16 v[98:101], v[164:167], v[216:219], v[98:101]
	s_setprio 0
	s_setprio 1
	v_mfma_f32_16x16x32_bf16 v[62:65], v[168:171], v[188:191], v[62:65]
	v_mfma_f32_16x16x32_bf16 v[58:61], v[180:183], v[188:191], v[58:61]
	v_mfma_f32_16x16x32_bf16 v[54:57], v[168:171], v[196:199], v[54:57]
	v_mfma_f32_16x16x32_bf16 v[50:53], v[180:183], v[196:199], v[50:53]
	v_mfma_f32_16x16x32_bf16 v[46:49], v[168:171], v[204:207], v[46:49]
	v_mfma_f32_16x16x32_bf16 v[42:45], v[180:183], v[204:207], v[42:45]
	v_mfma_f32_16x16x32_bf16 v[38:41], v[168:171], v[212:215], v[38:41]
	v_mfma_f32_16x16x32_bf16 v[34:37], v[180:183], v[212:215], v[34:37]
	v_mfma_f32_16x16x32_bf16 v[62:65], v[172:175], v[192:195], v[62:65]
	v_mfma_f32_16x16x32_bf16 v[58:61], v[184:187], v[192:195], v[58:61]
	v_mfma_f32_16x16x32_bf16 v[54:57], v[172:175], v[200:203], v[54:57]
	v_mfma_f32_16x16x32_bf16 v[50:53], v[184:187], v[200:203], v[50:53]
	v_mfma_f32_16x16x32_bf16 v[46:49], v[172:175], v[208:211], v[46:49]
	v_mfma_f32_16x16x32_bf16 v[42:45], v[184:187], v[208:211], v[42:45]
	v_mfma_f32_16x16x32_bf16 v[38:41], v[172:175], v[216:219], v[38:41]
	v_mfma_f32_16x16x32_bf16 v[34:37], v[184:187], v[216:219], v[34:37]
	s_setprio 0
	s_barrier
	s_add_i32 s33, s33, s68
	v_lshl_add_u64 v[176:177], v[176:177], 0, s[74:75]
	s_mov_b32 m0, s33
	ds_read_b128 v[188:191], v153 offset:49152
	ds_read_b128 v[192:195], v153 offset:50176
	ds_read_b128 v[196:199], v153 offset:51200
	ds_read_b128 v[200:203], v153 offset:52224
	ds_read_b128 v[204:207], v153 offset:53248
	ds_read_b128 v[208:211], v153 offset:54272
	ds_read_b128 v[212:215], v153 offset:55296
	ds_read_b128 v[216:219], v153 offset:56320
	global_load_lds_dwordx4 v[176:177], off
	s_add_i32 m0, s33, 0x2000
	s_add_u32 s36, s36, 0x40080
	v_lshl_add_u64 v[176:177], v[220:221], 0, s[74:75]
	s_addc_u32 s37, s37, 0
	s_add_i32 s33, s43, s68
	global_load_lds_dwordx4 v[176:177], off
	v_lshl_add_u64 v[176:177], s[36:37], 0, v[0:1]
	s_mov_b32 m0, s33
	s_nop 0
	global_load_lds_dwordx4 v[176:177], off
	v_lshl_add_u64 v[176:177], s[36:37], 0, v[138:139]
	s_add_i32 m0, s33, 0x2000
	s_nop 0
	global_load_lds_dwordx4 v[176:177], off
	v_lshl_add_u64 v[176:177], v[222:223], 0, s[74:75]
	s_mov_b32 m0, s86
	s_nop 0
	global_load_lds_dwordx4 v[176:177], off
	v_lshl_add_u64 v[176:177], v[224:225], 0, s[74:75]
	s_mov_b32 m0, s87
	s_nop 0
	global_load_lds_dwordx4 v[176:177], off
	s_waitcnt vmcnt(8)
	s_waitcnt lgkmcnt(0)
	s_barrier
	s_setprio 1
	s_waitcnt lgkmcnt(0)
	v_mfma_f32_16x16x32_bf16 v[94:97], v[130:133], v[188:191], v[94:97]
	v_mfma_f32_16x16x32_bf16 v[90:93], v[160:163], v[188:191], v[90:93]
	v_mfma_f32_16x16x32_bf16 v[86:89], v[130:133], v[196:199], v[86:89]
	v_mfma_f32_16x16x32_bf16 v[82:85], v[160:163], v[196:199], v[82:85]
	v_mfma_f32_16x16x32_bf16 v[78:81], v[130:133], v[204:207], v[78:81]
	v_mfma_f32_16x16x32_bf16 v[74:77], v[160:163], v[204:207], v[74:77]
	v_mfma_f32_16x16x32_bf16 v[70:73], v[130:133], v[212:215], v[70:73]
	v_mfma_f32_16x16x32_bf16 v[66:69], v[160:163], v[212:215], v[66:69]
	v_mfma_f32_16x16x32_bf16 v[94:97], v[156:159], v[192:195], v[94:97]
	v_mfma_f32_16x16x32_bf16 v[90:93], v[164:167], v[192:195], v[90:93]
	v_mfma_f32_16x16x32_bf16 v[86:89], v[156:159], v[200:203], v[86:89]
	v_mfma_f32_16x16x32_bf16 v[82:85], v[164:167], v[200:203], v[82:85]
	v_mfma_f32_16x16x32_bf16 v[78:81], v[156:159], v[208:211], v[78:81]
	v_mfma_f32_16x16x32_bf16 v[74:77], v[164:167], v[208:211], v[74:77]
	v_mfma_f32_16x16x32_bf16 v[70:73], v[156:159], v[216:219], v[70:73]
	v_mfma_f32_16x16x32_bf16 v[66:69], v[164:167], v[216:219], v[66:69]
	s_setprio 0
	s_setprio 1
	v_mfma_f32_16x16x32_bf16 v[30:33], v[168:171], v[188:191], v[30:33]
	v_mfma_f32_16x16x32_bf16 v[26:29], v[180:183], v[188:191], v[26:29]
	v_mfma_f32_16x16x32_bf16 v[22:25], v[168:171], v[196:199], v[22:25]
	v_mfma_f32_16x16x32_bf16 v[18:21], v[180:183], v[196:199], v[18:21]
	v_mfma_f32_16x16x32_bf16 v[14:17], v[168:171], v[204:207], v[14:17]
	v_mfma_f32_16x16x32_bf16 v[10:13], v[180:183], v[204:207], v[10:13]
	v_mfma_f32_16x16x32_bf16 v[6:9], v[168:171], v[212:215], v[6:9]
	v_mfma_f32_16x16x32_bf16 v[2:5], v[180:183], v[212:215], v[2:5]
	v_mfma_f32_16x16x32_bf16 v[30:33], v[172:175], v[192:195], v[30:33]
	v_mfma_f32_16x16x32_bf16 v[26:29], v[184:187], v[192:195], v[26:29]
	v_mfma_f32_16x16x32_bf16 v[22:25], v[172:175], v[200:203], v[22:25]
	v_mfma_f32_16x16x32_bf16 v[18:21], v[184:187], v[200:203], v[18:21]
	v_mfma_f32_16x16x32_bf16 v[14:17], v[172:175], v[208:211], v[14:17]
	v_mfma_f32_16x16x32_bf16 v[10:13], v[184:187], v[208:211], v[10:13]
	v_mfma_f32_16x16x32_bf16 v[6:9], v[172:175], v[216:219], v[6:9]
	v_mfma_f32_16x16x32_bf16 v[2:5], v[184:187], v[216:219], v[2:5]
	s_setprio 0
	s_barrier
	s_add_i32 s42, s42, 2
	s_add_u32 s30, s30, 0x100
	s_addc_u32 s31, s31, 0
	s_add_u32 s25, s25, 0x100
	s_addc_u32 s35, s35, 0
	s_cmp_gt_u32 s42, 13
	s_cbranch_scc0 .LBB0_708
	s_and_b64 vcc, exec, s[20:21]
	s_cbranch_vccz .LBB0_711
	s_barrier
